# gdn_scan: the count-equalising load of waves 4-7 reads one cached dword instead of a scattered line set
# speedup vs baseline: 1.0047x; 1.0047x over previous
.Lscp_nou:
	global_load_dword v119, v177, s[90:91]
